# GEMM K-loops: removed the back-to-back s_setprio 0/1 flip in the middle of each 32-MFMA segment (two wasted issue slots per phase)
# baseline (speedup 1.0000x reference)
; #define PG8_STAGE(bufoff, gbase, voff) do { _Pragma("unroll") for (int _i = 0; _i < 2; ++_i) \
;         __builtin_amdgcn_global_load_lds((const unsigned*)((const char*)(gbase) + (voff)[_i]), (LAS unsigned*)(lds + (bufoff) + ldsw + _i * 8192), 16, 0, 0); } while (0)
; #define PG8_LDA(dst, b, h) do { _Pragma("unroll") for (int m = 0; m < 4; ++m) _Pragma("unroll") for (int k = 0; k < 2; ++k) dst[m][k] = *(const LAS bf16x8*)(lds + PG8_SA(b, h) + aoff + m * 2048 + k * 1024); } while (0)
; #define PG8_LDB(dst, b, h) do { _Pragma("unroll") for (int n = 0; n < 2; ++n) _Pragma("unroll") for (int k = 0; k < 2; ++k) dst[n][k] = *(const LAS bf16x8*)(lds + PG8_SB(b, h) + boff + n * 2048 + k * 1024); } while (0)
; #define PG8_MMA(ai, bj, At, Bt) do { __builtin_amdgcn_s_setprio(1); _Pragma("unroll") for (int m = 0; m < 4; ++m) _Pragma("unroll") for (int n = 0; n < 2; ++n) _Pragma("unroll") for (int k = 0; k < 2; ++k) \
;         acc[ai][bj][m][n] = __builtin_amdgcn_mfma_f32_16x16x32_bf16(Bt[n][k], At[m][k], acc[ai][bj][m][n], 0, 0, 0); __builtin_amdgcn_s_setprio(0); } while (0)
; #define PG8_WAIT_V(n) asm volatile("s_waitcnt vmcnt(" #n ")" ::: "memory")
; #define PG8_WAIT_L(n) asm volatile("s_waitcnt lgkmcnt(" #n ")" ::: "memory")
; #define PG8_BAR __builtin_amdgcn_s_barrier()
; #define PG8_SCHED __builtin_amdgcn_sched_barrier(0)
; template <class Epi, class Sched, bool ALIGN_EPI>
; __device__ __forceinline__ void gemm_phase(LAS unsigned char* lds, const Gemm g, const Sched& S, const Epi& E, const int tid) {
;     ...
;             PG8_LDB(B0, 0, 0); PG8_LDB(B1, 0, 1); PG8_SCHED; PG8_LDA(At, 0, 0); PG8_STAGE(PG8_SA(1, 1), a1 + hstepA, voffA);
;             PG8_WAIT_V(8); PG8_WAIT_L(0); PG8_BAR; PG8_MMA(0, 0, At, B0); PG8_MMA(0, 1, At, B1); PG8_BAR; PG8_SCHED;
;             PG8_LDA(At, 0, 1); PG8_STAGE(PG8_SB(0, 0), b2, voffB); PG8_STAGE(PG8_SB(0, 1), b2 + hstepB, voffB); PG8_STAGE(PG8_SA(0, 0), a2, voffA);
;             PG8_WAIT_V(8); PG8_WAIT_L(0); PG8_BAR; PG8_MMA(1, 0, At, B0); PG8_MMA(1, 1, At, B1); PG8_BAR; PG8_SCHED;
;             PG8_LDB(B0, 1, 0); PG8_LDB(B1, 1, 1); PG8_SCHED; PG8_LDA(At, 1, 0); PG8_STAGE(PG8_SA(0, 1), a2 + hstepA, voffA);
.LBB0_71:
	s_add_u32 s52, s50, 0xfffc0080
	s_addc_u32 s53, s51, -1
	s_add_i32 s74, 0, 0x10000
	s_cmp_eq_u32 s73, 12
	s_cselect_b32 s55, s41, s53
	s_cselect_b32 s54, s47, s52
	s_cselect_b32 s53, s39, s72
	s_cselect_b32 s52, s49, s71
	s_add_i32 s76, 0, 0x14000
	v_add_u32_e32 v84, s74, v190
	v_add_u32_e32 v136, s76, v190
	ds_read_b128 v[64:67], v84
	ds_read_b128 v[68:71], v84 offset:1024
	ds_read_b128 v[80:83], v84 offset:2048
	ds_read_b128 v[84:87], v84 offset:3072
	ds_read_b128 v[88:91], v136
	ds_read_b128 v[92:95], v136 offset:1024
	ds_read_b128 v[132:135], v136 offset:2048
	ds_read_b128 v[136:139], v136 offset:3072
	v_lshl_add_u64 v[220:221], s[50:51], 0, v[178:179]
	s_add_i32 m0, s61, 0xc000
	ds_read_b128 v[160:163], v193
	ds_read_b128 v[182:185], v193 offset:1024
	ds_read_b128 v[186:189], v193 offset:2048
	ds_read_b128 v[194:197], v193 offset:3072
	ds_read_b128 v[198:201], v193 offset:4096
	ds_read_b128 v[202:205], v193 offset:5120
	ds_read_b128 v[210:213], v193 offset:6144
	ds_read_b128 v[216:219], v193 offset:7168
	global_load_lds_dwordx4 v[220:221], off
	v_lshl_add_u64 v[220:221], s[50:51], 0, v[180:181]
	s_add_i32 m0, s61, 0xe000
	s_nop 0
	global_load_lds_dwordx4 v[220:221], off
	s_waitcnt vmcnt(8)
	s_waitcnt lgkmcnt(0)
	s_barrier
	s_setprio 1
	s_waitcnt lgkmcnt(0)
	v_mfma_f32_16x16x32_bf16 v[148:151], v[64:67], v[160:163], v[148:151]
	v_mfma_f32_16x16x32_bf16 v[140:143], v[80:83], v[160:163], v[140:143]
	v_mfma_f32_16x16x32_bf16 v[124:127], v[64:67], v[186:189], v[124:127]
	v_mfma_f32_16x16x32_bf16 v[116:119], v[80:83], v[186:189], v[116:119]
	v_mfma_f32_16x16x32_bf16 v[108:111], v[64:67], v[198:201], v[108:111]
	v_mfma_f32_16x16x32_bf16 v[100:103], v[80:83], v[198:201], v[100:103]
	v_mfma_f32_16x16x32_bf16 v[104:107], v[64:67], v[210:213], v[104:107]
	v_mfma_f32_16x16x32_bf16 v[76:79], v[80:83], v[210:213], v[76:79]
	v_mfma_f32_16x16x32_bf16 v[148:151], v[68:71], v[182:185], v[148:151]
	v_mfma_f32_16x16x32_bf16 v[140:143], v[84:87], v[182:185], v[140:143]
	v_mfma_f32_16x16x32_bf16 v[124:127], v[68:71], v[194:197], v[124:127]
	v_mfma_f32_16x16x32_bf16 v[116:119], v[84:87], v[194:197], v[116:119]
	v_mfma_f32_16x16x32_bf16 v[108:111], v[68:71], v[202:205], v[108:111]
	v_mfma_f32_16x16x32_bf16 v[100:103], v[84:87], v[202:205], v[100:103]
	v_mfma_f32_16x16x32_bf16 v[104:107], v[68:71], v[216:219], v[104:107]
	v_mfma_f32_16x16x32_bf16 v[76:79], v[84:87], v[216:219], v[76:79]
	v_mfma_f32_16x16x32_bf16 v[156:159], v[88:91], v[160:163], v[156:159]
	v_mfma_f32_16x16x32_bf16 v[152:155], v[132:135], v[160:163], v[152:155]
	v_mfma_f32_16x16x32_bf16 v[144:147], v[88:91], v[186:189], v[144:147]
	v_mfma_f32_16x16x32_bf16 v[128:131], v[132:135], v[186:189], v[128:131]
	v_mfma_f32_16x16x32_bf16 v[120:123], v[88:91], v[198:201], v[120:123]
	v_mfma_f32_16x16x32_bf16 v[112:115], v[132:135], v[198:201], v[112:115]
	v_mfma_f32_16x16x32_bf16 v[96:99], v[88:91], v[210:213], v[96:99]
	v_mfma_f32_16x16x32_bf16 v[72:75], v[132:135], v[210:213], v[72:75]
	v_mfma_f32_16x16x32_bf16 v[156:159], v[92:95], v[182:185], v[156:159]
	v_mfma_f32_16x16x32_bf16 v[152:155], v[136:139], v[182:185], v[152:155]
	v_mfma_f32_16x16x32_bf16 v[144:147], v[92:95], v[194:197], v[144:147]
	v_mfma_f32_16x16x32_bf16 v[128:131], v[136:139], v[194:197], v[128:131]
	v_mfma_f32_16x16x32_bf16 v[120:123], v[92:95], v[202:205], v[120:123]
	v_mfma_f32_16x16x32_bf16 v[112:115], v[136:139], v[202:205], v[112:115]
	v_mfma_f32_16x16x32_bf16 v[96:99], v[92:95], v[216:219], v[96:99]
	v_mfma_f32_16x16x32_bf16 v[72:75], v[136:139], v[216:219], v[72:75]
	s_setprio 0
	s_barrier
	s_add_i32 s74, s74, s60
	v_lshl_add_u64 v[220:221], s[52:53], 0, v[164:165]
	s_mov_b32 m0, s74
	ds_read_b128 v[160:163], v193 offset:16384
	ds_read_b128 v[182:185], v193 offset:17408
	ds_read_b128 v[186:189], v193 offset:18432
	ds_read_b128 v[194:197], v193 offset:19456
	ds_read_b128 v[198:201], v193 offset:20480
	ds_read_b128 v[202:205], v193 offset:21504
	ds_read_b128 v[210:213], v193 offset:22528
	ds_read_b128 v[216:219], v193 offset:23552
	global_load_lds_dwordx4 v[220:221], off
	s_add_i32 m0, s74, 0x2000
	s_add_u32 s74, s52, 0x40000
	v_lshl_add_u64 v[222:223], s[52:53], 0, v[176:177]
	s_addc_u32 s75, s53, 0
	s_add_i32 s76, s76, s60
	global_load_lds_dwordx4 v[222:223], off
	v_lshl_add_u64 v[224:225], s[74:75], 0, v[164:165]
	s_mov_b32 m0, s76
	v_lshl_add_u64 v[226:227], s[54:55], 0, v[174:175]
	global_load_lds_dwordx4 v[224:225], off
	v_lshl_add_u64 v[224:225], s[74:75], 0, v[176:177]
	s_add_i32 m0, s76, 0x2000
	s_nop 0
	global_load_lds_dwordx4 v[224:225], off
	v_lshl_add_u64 v[224:225], s[54:55], 0, v[172:173]
	s_mov_b32 m0, s61
	s_nop 0
	global_load_lds_dwordx4 v[224:225], off
	s_mov_b32 m0, s62
	s_nop 0
	global_load_lds_dwordx4 v[226:227], off
	s_waitcnt vmcnt(8)
	s_waitcnt lgkmcnt(0)
	s_barrier
; #define PG8_STAGE(bufoff, gbase, voff) do { _Pragma("unroll") for (int _i = 0; _i < 2; ++_i) \
;         __builtin_amdgcn_global_load_lds((const unsigned*)((const char*)(gbase) + (voff)[_i]), (LAS unsigned*)(lds + (bufoff) + ldsw + _i * 8192), 16, 0, 0); } while (0)
; #define PG8_LDA(dst, b, h) do { _Pragma("unroll") for (int m = 0; m < 4; ++m) _Pragma("unroll") for (int k = 0; k < 2; ++k) dst[m][k] = *(const LAS bf16x8*)(lds + PG8_SA(b, h) + aoff + m * 2048 + k * 1024); } while (0)
; #define PG8_LDB(dst, b, h) do { _Pragma("unroll") for (int n = 0; n < 2; ++n) _Pragma("unroll") for (int k = 0; k < 2; ++k) dst[n][k] = *(const LAS bf16x8*)(lds + PG8_SB(b, h) + boff + n * 2048 + k * 1024); } while (0)
; #define PG8_MMA(ai, bj, At, Bt) do { __builtin_amdgcn_s_setprio(1); _Pragma("unroll") for (int m = 0; m < 4; ++m) _Pragma("unroll") for (int n = 0; n < 2; ++n) _Pragma("unroll") for (int k = 0; k < 2; ++k) \
;         acc[ai][bj][m][n] = __builtin_amdgcn_mfma_f32_16x16x32_bf16(Bt[n][k], At[m][k], acc[ai][bj][m][n], 0, 0, 0); __builtin_amdgcn_s_setprio(0); } while (0)
; #define PG8_WAIT_V(n) asm volatile("s_waitcnt vmcnt(" #n ")" ::: "memory")
; #define PG8_WAIT_L(n) asm volatile("s_waitcnt lgkmcnt(" #n ")" ::: "memory")
; #define PG8_BAR __builtin_amdgcn_s_barrier()
; #define PG8_SCHED __builtin_amdgcn_sched_barrier(0)
; template <class Epi, class Sched, bool ALIGN_EPI>
; __device__ __forceinline__ void gemm_phase(LAS unsigned char* lds, const Gemm g, const Sched& S, const Epi& E, const int tid) {
;     ...
;             PG8_WAIT_V(8); PG8_WAIT_L(0); PG8_BAR; PG8_MMA(1, 0, At, B0); PG8_MMA(1, 1, At, B1); PG8_BAR; PG8_SCHED;
;             PG8_LDB(B0, 1, 0); PG8_LDB(B1, 1, 1); PG8_SCHED; PG8_LDA(At, 1, 0); PG8_STAGE(PG8_SA(0, 1), a2 + hstepA, voffA);
;             PG8_WAIT_V(8); PG8_WAIT_L(0); PG8_BAR; PG8_MMA(0, 0, At, B0); PG8_MMA(0, 1, At, B1); PG8_BAR; PG8_SCHED;
	s_setprio 1
	s_waitcnt lgkmcnt(0)
	v_mfma_f32_16x16x32_bf16 v[52:55], v[64:67], v[160:163], v[52:55]
	v_mfma_f32_16x16x32_bf16 v[44:47], v[80:83], v[160:163], v[44:47]
	v_mfma_f32_16x16x32_bf16 v[36:39], v[64:67], v[186:189], v[36:39]
	v_mfma_f32_16x16x32_bf16 v[28:31], v[80:83], v[186:189], v[28:31]
	v_mfma_f32_16x16x32_bf16 v[24:27], v[64:67], v[198:201], v[24:27]
	v_mfma_f32_16x16x32_bf16 v[12:15], v[80:83], v[198:201], v[12:15]
	v_mfma_f32_16x16x32_bf16 v[16:19], v[64:67], v[210:213], v[16:19]
	v_mfma_f32_16x16x32_bf16 v[4:7], v[80:83], v[210:213], v[4:7]
	v_mfma_f32_16x16x32_bf16 v[52:55], v[68:71], v[182:185], v[52:55]
	v_mfma_f32_16x16x32_bf16 v[44:47], v[84:87], v[182:185], v[44:47]
	v_mfma_f32_16x16x32_bf16 v[36:39], v[68:71], v[194:197], v[36:39]
	v_mfma_f32_16x16x32_bf16 v[28:31], v[84:87], v[194:197], v[28:31]
	v_mfma_f32_16x16x32_bf16 v[24:27], v[68:71], v[202:205], v[24:27]
	v_mfma_f32_16x16x32_bf16 v[12:15], v[84:87], v[202:205], v[12:15]
	v_mfma_f32_16x16x32_bf16 v[16:19], v[68:71], v[216:219], v[16:19]
	v_mfma_f32_16x16x32_bf16 v[4:7], v[84:87], v[216:219], v[4:7]
	v_mfma_f32_16x16x32_bf16 v[60:63], v[88:91], v[160:163], v[60:63]
	v_mfma_f32_16x16x32_bf16 v[56:59], v[132:135], v[160:163], v[56:59]
	v_mfma_f32_16x16x32_bf16 v[48:51], v[88:91], v[186:189], v[48:51]
	v_mfma_f32_16x16x32_bf16 v[40:43], v[132:135], v[186:189], v[40:43]
	v_mfma_f32_16x16x32_bf16 v[32:35], v[88:91], v[198:201], v[32:35]
	v_mfma_f32_16x16x32_bf16 v[20:23], v[132:135], v[198:201], v[20:23]
	v_mfma_f32_16x16x32_bf16 v[8:11], v[88:91], v[210:213], v[8:11]
	v_mfma_f32_16x16x32_bf16 v[0:3], v[132:135], v[210:213], v[0:3]
	v_mfma_f32_16x16x32_bf16 v[60:63], v[92:95], v[182:185], v[60:63]
	v_mfma_f32_16x16x32_bf16 v[56:59], v[136:139], v[182:185], v[56:59]
	v_mfma_f32_16x16x32_bf16 v[48:51], v[92:95], v[194:197], v[48:51]
	v_mfma_f32_16x16x32_bf16 v[40:43], v[136:139], v[194:197], v[40:43]
	v_mfma_f32_16x16x32_bf16 v[32:35], v[92:95], v[202:205], v[32:35]
	v_mfma_f32_16x16x32_bf16 v[20:23], v[136:139], v[202:205], v[20:23]
	v_mfma_f32_16x16x32_bf16 v[8:11], v[92:95], v[216:219], v[8:11]
	v_mfma_f32_16x16x32_bf16 v[0:3], v[136:139], v[216:219], v[0:3]
	s_setprio 0
	s_barrier
	s_add_i32 s74, 0, 0x18000
	s_add_i32 s75, 0, 0x1c000
	v_add_u32_e32 v84, s74, v190
	v_add_u32_e32 v136, s75, v190
	ds_read_b128 v[64:67], v84
	ds_read_b128 v[68:71], v84 offset:1024
	ds_read_b128 v[80:83], v84 offset:2048
	ds_read_b128 v[84:87], v84 offset:3072
	ds_read_b128 v[88:91], v136
	ds_read_b128 v[92:95], v136 offset:1024
	ds_read_b128 v[132:135], v136 offset:2048
	ds_read_b128 v[136:139], v136 offset:3072
	s_add_u32 s54, s54, 0x40000
	s_addc_u32 s55, s55, 0
	s_mov_b32 m0, s63
	v_lshl_add_u64 v[228:229], s[54:55], 0, v[172:173]
	ds_read_b128 v[160:163], v193 offset:32768
	ds_read_b128 v[182:185], v193 offset:33792
	ds_read_b128 v[186:189], v193 offset:34816
	ds_read_b128 v[194:197], v193 offset:35840
	ds_read_b128 v[198:201], v193 offset:36864
	ds_read_b128 v[202:205], v193 offset:37888
	ds_read_b128 v[210:213], v193 offset:38912
	ds_read_b128 v[216:219], v193 offset:39936
	global_load_lds_dwordx4 v[228:229], off
	v_lshl_add_u64 v[228:229], s[54:55], 0, v[174:175]
	s_mov_b32 m0, s64
	s_nop 0
	global_load_lds_dwordx4 v[228:229], off
	s_waitcnt vmcnt(8)
	s_waitcnt lgkmcnt(0)
	s_barrier
	s_setprio 1
	s_waitcnt lgkmcnt(0)
	v_mfma_f32_16x16x32_bf16 v[148:151], v[64:67], v[160:163], v[148:151]
	v_mfma_f32_16x16x32_bf16 v[140:143], v[80:83], v[160:163], v[140:143]
	v_mfma_f32_16x16x32_bf16 v[124:127], v[64:67], v[186:189], v[124:127]
	v_mfma_f32_16x16x32_bf16 v[116:119], v[80:83], v[186:189], v[116:119]
	v_mfma_f32_16x16x32_bf16 v[108:111], v[64:67], v[198:201], v[108:111]
	v_mfma_f32_16x16x32_bf16 v[100:103], v[80:83], v[198:201], v[100:103]
	v_mfma_f32_16x16x32_bf16 v[104:107], v[64:67], v[210:213], v[104:107]
	v_mfma_f32_16x16x32_bf16 v[76:79], v[80:83], v[210:213], v[76:79]
	v_mfma_f32_16x16x32_bf16 v[148:151], v[68:71], v[182:185], v[148:151]
	v_mfma_f32_16x16x32_bf16 v[140:143], v[84:87], v[182:185], v[140:143]
	v_mfma_f32_16x16x32_bf16 v[124:127], v[68:71], v[194:197], v[124:127]
	v_mfma_f32_16x16x32_bf16 v[116:119], v[84:87], v[194:197], v[116:119]
	v_mfma_f32_16x16x32_bf16 v[108:111], v[68:71], v[202:205], v[108:111]
	v_mfma_f32_16x16x32_bf16 v[100:103], v[84:87], v[202:205], v[100:103]
	v_mfma_f32_16x16x32_bf16 v[104:107], v[68:71], v[216:219], v[104:107]
	v_mfma_f32_16x16x32_bf16 v[76:79], v[84:87], v[216:219], v[76:79]
	v_mfma_f32_16x16x32_bf16 v[156:159], v[88:91], v[160:163], v[156:159]
	v_mfma_f32_16x16x32_bf16 v[152:155], v[132:135], v[160:163], v[152:155]
	v_mfma_f32_16x16x32_bf16 v[144:147], v[88:91], v[186:189], v[144:147]
	v_mfma_f32_16x16x32_bf16 v[128:131], v[132:135], v[186:189], v[128:131]
	v_mfma_f32_16x16x32_bf16 v[120:123], v[88:91], v[198:201], v[120:123]
	v_mfma_f32_16x16x32_bf16 v[112:115], v[132:135], v[198:201], v[112:115]
	v_mfma_f32_16x16x32_bf16 v[96:99], v[88:91], v[210:213], v[96:99]
	v_mfma_f32_16x16x32_bf16 v[72:75], v[132:135], v[210:213], v[72:75]
	v_mfma_f32_16x16x32_bf16 v[156:159], v[92:95], v[182:185], v[156:159]
	v_mfma_f32_16x16x32_bf16 v[152:155], v[136:139], v[182:185], v[152:155]
	v_mfma_f32_16x16x32_bf16 v[144:147], v[92:95], v[194:197], v[144:147]
	v_mfma_f32_16x16x32_bf16 v[128:131], v[136:139], v[194:197], v[128:131]
	v_mfma_f32_16x16x32_bf16 v[120:123], v[92:95], v[202:205], v[120:123]
	v_mfma_f32_16x16x32_bf16 v[112:115], v[136:139], v[202:205], v[112:115]
	v_mfma_f32_16x16x32_bf16 v[96:99], v[92:95], v[216:219], v[96:99]
	v_mfma_f32_16x16x32_bf16 v[72:75], v[136:139], v[216:219], v[72:75]
	s_setprio 0
	s_barrier
; #define PG8_STAGE(bufoff, gbase, voff) do { _Pragma("unroll") for (int _i = 0; _i < 2; ++_i) \
;         __builtin_amdgcn_global_load_lds((const unsigned*)((const char*)(gbase) + (voff)[_i]), (LAS unsigned*)(lds + (bufoff) + ldsw + _i * 8192), 16, 0, 0); } while (0)
; #define PG8_LDA(dst, b, h) do { _Pragma("unroll") for (int m = 0; m < 4; ++m) _Pragma("unroll") for (int k = 0; k < 2; ++k) dst[m][k] = *(const LAS bf16x8*)(lds + PG8_SA(b, h) + aoff + m * 2048 + k * 1024); } while (0)
; #define PG8_MMA(ai, bj, At, Bt) do { __builtin_amdgcn_s_setprio(1); _Pragma("unroll") for (int m = 0; m < 4; ++m) _Pragma("unroll") for (int n = 0; n < 2; ++n) _Pragma("unroll") for (int k = 0; k < 2; ++k) \
;         acc[ai][bj][m][n] = __builtin_amdgcn_mfma_f32_16x16x32_bf16(Bt[n][k], At[m][k], acc[ai][bj][m][n], 0, 0, 0); __builtin_amdgcn_s_setprio(0); } while (0)
; #define PG8_WAIT_V(n) asm volatile("s_waitcnt vmcnt(" #n ")" ::: "memory")
; #define PG8_WAIT_L(n) asm volatile("s_waitcnt lgkmcnt(" #n ")" ::: "memory")
; #define PG8_BAR __builtin_amdgcn_s_barrier()
; #define PG8_SCHED __builtin_amdgcn_sched_barrier(0)
; template <class Epi, class Sched, bool ALIGN_EPI>
; __device__ __forceinline__ void gemm_phase(LAS unsigned char* lds, const Gemm g, const Sched& S, const Epi& E, const int tid) {
;     ...
;             PG8_LDA(At, 1, 1); PG8_STAGE(PG8_SB(1, 0), b3, voffB); PG8_STAGE(PG8_SB(1, 1), b3 + hstepB, voffB); PG8_STAGE(PG8_SA(1, 0), a3, voffA);
;             PG8_WAIT_V(8); PG8_WAIT_L(0); PG8_BAR; PG8_MMA(1, 0, At, B0); PG8_MMA(1, 1, At, B1); PG8_BAR; PG8_SCHED;
;         }
;         if constexpr (ALIGN_EPI) { if (wr == 0) PG8_BAR; }
	s_add_i32 s54, s74, s60
	v_lshl_add_u64 v[220:221], v[220:221], 0, s[2:3]
	s_mov_b32 m0, s54
	ds_read_b128 v[160:163], v193 offset:49152
	ds_read_b128 v[182:185], v193 offset:50176
	ds_read_b128 v[186:189], v193 offset:51200
	ds_read_b128 v[194:197], v193 offset:52224
	ds_read_b128 v[198:201], v193 offset:53248
	ds_read_b128 v[202:205], v193 offset:54272
	ds_read_b128 v[210:213], v193 offset:55296
	ds_read_b128 v[216:219], v193 offset:56320
	global_load_lds_dwordx4 v[220:221], off
	s_add_i32 m0, s54, 0x2000
	s_add_u32 s52, s52, 0x40080
	v_lshl_add_u64 v[220:221], v[222:223], 0, s[2:3]
	s_addc_u32 s53, s53, 0
	s_add_i32 s54, s75, s60
	global_load_lds_dwordx4 v[220:221], off
	v_lshl_add_u64 v[220:221], s[52:53], 0, v[164:165]
	s_mov_b32 m0, s54
	s_nop 0
	global_load_lds_dwordx4 v[220:221], off
	v_lshl_add_u64 v[220:221], s[52:53], 0, v[176:177]
	s_add_i32 m0, s54, 0x2000
	s_nop 0
	global_load_lds_dwordx4 v[220:221], off
	v_lshl_add_u64 v[220:221], v[224:225], 0, s[2:3]
	s_mov_b32 m0, s65
	s_nop 0
	global_load_lds_dwordx4 v[220:221], off
	v_lshl_add_u64 v[220:221], v[226:227], 0, s[2:3]
	s_mov_b32 m0, s66
	s_nop 0
	global_load_lds_dwordx4 v[220:221], off
	s_waitcnt vmcnt(8)
	s_waitcnt lgkmcnt(0)
	s_barrier
	s_setprio 1
	s_waitcnt lgkmcnt(0)
	v_mfma_f32_16x16x32_bf16 v[52:55], v[64:67], v[160:163], v[52:55]
	v_mfma_f32_16x16x32_bf16 v[44:47], v[80:83], v[160:163], v[44:47]
	v_mfma_f32_16x16x32_bf16 v[36:39], v[64:67], v[186:189], v[36:39]
	v_mfma_f32_16x16x32_bf16 v[28:31], v[80:83], v[186:189], v[28:31]
	v_mfma_f32_16x16x32_bf16 v[24:27], v[64:67], v[198:201], v[24:27]
	v_mfma_f32_16x16x32_bf16 v[12:15], v[80:83], v[198:201], v[12:15]
	v_mfma_f32_16x16x32_bf16 v[16:19], v[64:67], v[210:213], v[16:19]
	v_mfma_f32_16x16x32_bf16 v[4:7], v[80:83], v[210:213], v[4:7]
	v_mfma_f32_16x16x32_bf16 v[52:55], v[68:71], v[182:185], v[52:55]
	v_mfma_f32_16x16x32_bf16 v[44:47], v[84:87], v[182:185], v[44:47]
	v_mfma_f32_16x16x32_bf16 v[36:39], v[68:71], v[194:197], v[36:39]
	v_mfma_f32_16x16x32_bf16 v[28:31], v[84:87], v[194:197], v[28:31]
	v_mfma_f32_16x16x32_bf16 v[24:27], v[68:71], v[202:205], v[24:27]
	v_mfma_f32_16x16x32_bf16 v[12:15], v[84:87], v[202:205], v[12:15]
	v_mfma_f32_16x16x32_bf16 v[16:19], v[68:71], v[216:219], v[16:19]
	v_mfma_f32_16x16x32_bf16 v[4:7], v[84:87], v[216:219], v[4:7]
	v_mfma_f32_16x16x32_bf16 v[60:63], v[88:91], v[160:163], v[60:63]
	v_mfma_f32_16x16x32_bf16 v[56:59], v[132:135], v[160:163], v[56:59]
	v_mfma_f32_16x16x32_bf16 v[48:51], v[88:91], v[186:189], v[48:51]
	v_mfma_f32_16x16x32_bf16 v[40:43], v[132:135], v[186:189], v[40:43]
	v_mfma_f32_16x16x32_bf16 v[32:35], v[88:91], v[198:201], v[32:35]
	v_mfma_f32_16x16x32_bf16 v[20:23], v[132:135], v[198:201], v[20:23]
	v_mfma_f32_16x16x32_bf16 v[8:11], v[88:91], v[210:213], v[8:11]
	v_mfma_f32_16x16x32_bf16 v[0:3], v[132:135], v[210:213], v[0:3]
	v_mfma_f32_16x16x32_bf16 v[60:63], v[92:95], v[182:185], v[60:63]
	v_mfma_f32_16x16x32_bf16 v[56:59], v[136:139], v[182:185], v[56:59]
	v_mfma_f32_16x16x32_bf16 v[48:51], v[92:95], v[194:197], v[48:51]
	v_mfma_f32_16x16x32_bf16 v[40:43], v[136:139], v[194:197], v[40:43]
	v_mfma_f32_16x16x32_bf16 v[32:35], v[92:95], v[202:205], v[32:35]
	v_mfma_f32_16x16x32_bf16 v[20:23], v[136:139], v[202:205], v[20:23]
	v_mfma_f32_16x16x32_bf16 v[8:11], v[92:95], v[216:219], v[8:11]
	v_mfma_f32_16x16x32_bf16 v[0:3], v[136:139], v[216:219], v[0:3]
	s_setprio 0
	s_barrier
	s_add_i32 s73, s73, 2
	s_add_u32 s50, s50, 0x100
	s_addc_u32 s51, s51, 0
	s_add_u32 s71, s71, 0x100
	s_addc_u32 s72, s72, 0
	s_cmp_gt_u32 s73, 13
	s_cbranch_scc0 .LBB0_71
	s_and_b64 vcc, exec, s[30:31]
	s_cbranch_vccz .LBB0_74
	s_barrier

; #define PG8_STAGE(bufoff, gbase, voff) do { _Pragma("unroll") for (int _i = 0; _i < 2; ++_i) \
;         __builtin_amdgcn_global_load_lds((const unsigned*)((const char*)(gbase) + (voff)[_i]), (LAS unsigned*)(lds + (bufoff) + ldsw + _i * 8192), 16, 0, 0); } while (0)
; #define PG8_LDA(dst, b, h) do { _Pragma("unroll") for (int m = 0; m < 4; ++m) _Pragma("unroll") for (int k = 0; k < 2; ++k) dst[m][k] = *(const LAS bf16x8*)(lds + PG8_SA(b, h) + aoff + m * 2048 + k * 1024); } while (0)
; #define PG8_LDB(dst, b, h) do { _Pragma("unroll") for (int n = 0; n < 2; ++n) _Pragma("unroll") for (int k = 0; k < 2; ++k) dst[n][k] = *(const LAS bf16x8*)(lds + PG8_SB(b, h) + boff + n * 2048 + k * 1024); } while (0)
; #define PG8_MMA(ai, bj, At, Bt) do { __builtin_amdgcn_s_setprio(1); _Pragma("unroll") for (int m = 0; m < 4; ++m) _Pragma("unroll") for (int n = 0; n < 2; ++n) _Pragma("unroll") for (int k = 0; k < 2; ++k) \
;         acc[ai][bj][m][n] = __builtin_amdgcn_mfma_f32_16x16x32_bf16(Bt[n][k], At[m][k], acc[ai][bj][m][n], 0, 0, 0); __builtin_amdgcn_s_setprio(0); } while (0)
; #define PG8_WAIT_V(n) asm volatile("s_waitcnt vmcnt(" #n ")" ::: "memory")
; #define PG8_WAIT_L(n) asm volatile("s_waitcnt lgkmcnt(" #n ")" ::: "memory")
; template <class Epi, class Sched, bool ALIGN_EPI>
; __device__ __forceinline__ void gemm_phase(LAS unsigned char* lds, const Gemm g, const Sched& S, const Epi& E, const int tid) {
;     ...
;         const bool has_next = S.next(ui + 1, nxt);
;         const char* nA = has_next ? (const char*)g.A + (size_t)nxt.pm * tstepA : cA; const char* nB = has_next ? (const char*)g.Bt + (size_t)nxt.pn * tstepB : cB;
;         for (int t = 0; t < nt; t += 2) {
;             const bool last = (t == nt - 2);
;             const char* a1 = cA + (size_t)(t + 1) * kstep;
;             const char* a2 = last ? nA : cA + (size_t)(t + 2) * kstep; const char* b2 = last ? nB : cB + (size_t)(t + 2) * kstep;
;             const char* a3 = a2 + kstep; const char* b3 = b2 + kstep;
;             PG8_LDB(B0, 0, 0); PG8_LDB(B1, 0, 1); PG8_SCHED; PG8_LDA(At, 0, 0); PG8_STAGE(PG8_SA(1, 1), a1 + hstepA, voffA);
;             PG8_WAIT_V(8); PG8_WAIT_L(0); PG8_BAR; PG8_MMA(0, 0, At, B0); PG8_MMA(0, 1, At, B1); PG8_BAR; PG8_SCHED;
;             PG8_LDA(At, 0, 1); PG8_STAGE(PG8_SB(0, 0), b2, voffB); PG8_STAGE(PG8_SB(0, 1), b2 + hstepB, voffB); PG8_STAGE(PG8_SA(0, 0), a2, voffA);
.LBB0_356:
	s_add_i32 s74, s28, 2
	s_add_u32 s10, s12, 0x100
	s_addc_u32 s11, s13, 0
	s_add_i32 s75, 0, 0x10000
	s_cmp_eq_u32 s67, s28
	s_cselect_b32 s29, s25, s11
	s_cselect_b32 s28, s24, s10
	s_cselect_b32 s77, s27, s73
	s_cselect_b32 s76, s26, s31
	s_add_i32 s78, 0, 0x14000
	v_add_u32_e32 v160, s75, v189
	v_add_u32_e32 v164, s78, v189
	ds_read_b128 v[128:131], v160
	ds_read_b128 v[132:135], v160 offset:1024
	ds_read_b128 v[156:159], v160 offset:2048
	ds_read_b128 v[160:163], v160 offset:3072
	ds_read_b128 v[172:175], v164
	ds_read_b128 v[176:179], v164 offset:1024
	ds_read_b128 v[190:193], v164 offset:2048
	ds_read_b128 v[194:197], v164 offset:3072
	v_lshl_add_u64 v[202:203], s[12:13], 0, v[142:143]
	s_add_i32 m0, s58, 0xc000
	ds_read_b128 v[198:201], v147
	ds_read_b128 v[216:219], v147 offset:1024
	ds_read_b128 v[220:223], v147 offset:2048
	ds_read_b128 v[224:227], v147 offset:3072
	ds_read_b128 v[228:231], v147 offset:4096
	ds_read_b128 v[232:235], v147 offset:5120
	ds_read_b128 v[236:239], v147 offset:6144
	ds_read_b128 v[240:243], v147 offset:7168
	global_load_lds_dwordx4 v[202:203], off
	v_lshl_add_u64 v[202:203], s[12:13], 0, v[144:145]
	s_add_i32 m0, s58, 0xe000
	s_nop 0
	global_load_lds_dwordx4 v[202:203], off
	s_waitcnt vmcnt(8)
	s_waitcnt lgkmcnt(0)
	s_barrier
	s_setprio 1
	s_waitcnt lgkmcnt(0)
	v_mfma_f32_16x16x32_bf16 v[124:127], v[128:131], v[198:201], v[124:127]
	v_mfma_f32_16x16x32_bf16 v[120:123], v[156:159], v[198:201], v[120:123]
	v_mfma_f32_16x16x32_bf16 v[116:119], v[128:131], v[220:223], v[116:119]
	v_mfma_f32_16x16x32_bf16 v[112:115], v[156:159], v[220:223], v[112:115]
	v_mfma_f32_16x16x32_bf16 v[108:111], v[128:131], v[228:231], v[108:111]
	v_mfma_f32_16x16x32_bf16 v[104:107], v[156:159], v[228:231], v[104:107]
	v_mfma_f32_16x16x32_bf16 v[100:103], v[128:131], v[236:239], v[100:103]
	v_mfma_f32_16x16x32_bf16 v[96:99], v[156:159], v[236:239], v[96:99]
	v_mfma_f32_16x16x32_bf16 v[124:127], v[132:135], v[216:219], v[124:127]
	v_mfma_f32_16x16x32_bf16 v[120:123], v[160:163], v[216:219], v[120:123]
	v_mfma_f32_16x16x32_bf16 v[116:119], v[132:135], v[224:227], v[116:119]
	v_mfma_f32_16x16x32_bf16 v[112:115], v[160:163], v[224:227], v[112:115]
	v_mfma_f32_16x16x32_bf16 v[108:111], v[132:135], v[232:235], v[108:111]
	v_mfma_f32_16x16x32_bf16 v[104:107], v[160:163], v[232:235], v[104:107]
	v_mfma_f32_16x16x32_bf16 v[100:103], v[132:135], v[240:243], v[100:103]
	v_mfma_f32_16x16x32_bf16 v[96:99], v[160:163], v[240:243], v[96:99]
	v_mfma_f32_16x16x32_bf16 v[60:63], v[172:175], v[198:201], v[60:63]
	v_mfma_f32_16x16x32_bf16 v[56:59], v[190:193], v[198:201], v[56:59]
	v_mfma_f32_16x16x32_bf16 v[52:55], v[172:175], v[220:223], v[52:55]
	v_mfma_f32_16x16x32_bf16 v[48:51], v[190:193], v[220:223], v[48:51]
	v_mfma_f32_16x16x32_bf16 v[44:47], v[172:175], v[228:231], v[44:47]
	v_mfma_f32_16x16x32_bf16 v[40:43], v[190:193], v[228:231], v[40:43]
	v_mfma_f32_16x16x32_bf16 v[36:39], v[172:175], v[236:239], v[36:39]
	v_mfma_f32_16x16x32_bf16 v[32:35], v[190:193], v[236:239], v[32:35]
	v_mfma_f32_16x16x32_bf16 v[60:63], v[176:179], v[216:219], v[60:63]
	v_mfma_f32_16x16x32_bf16 v[56:59], v[194:197], v[216:219], v[56:59]
	v_mfma_f32_16x16x32_bf16 v[52:55], v[176:179], v[224:227], v[52:55]
	v_mfma_f32_16x16x32_bf16 v[48:51], v[194:197], v[224:227], v[48:51]
	v_mfma_f32_16x16x32_bf16 v[44:47], v[176:179], v[232:235], v[44:47]
	v_mfma_f32_16x16x32_bf16 v[40:43], v[194:197], v[232:235], v[40:43]
	v_mfma_f32_16x16x32_bf16 v[36:39], v[176:179], v[240:243], v[36:39]
	v_mfma_f32_16x16x32_bf16 v[32:35], v[194:197], v[240:243], v[32:35]
	s_setprio 0
	s_barrier
	s_add_i32 s12, s75, s57
	v_lshl_add_u64 v[202:203], s[76:77], 0, v[148:149]
	s_mov_b32 m0, s12
	ds_read_b128 v[198:201], v147 offset:16384
	ds_read_b128 v[216:219], v147 offset:17408
	ds_read_b128 v[220:223], v147 offset:18432
	ds_read_b128 v[224:227], v147 offset:19456
	ds_read_b128 v[228:231], v147 offset:20480
	ds_read_b128 v[232:235], v147 offset:21504
	ds_read_b128 v[236:239], v147 offset:22528
	ds_read_b128 v[240:243], v147 offset:23552
	global_load_lds_dwordx4 v[202:203], off
	s_add_i32 m0, s12, 0x2000
	s_add_u32 s12, s76, s55
	v_lshl_add_u64 v[204:205], s[76:77], 0, v[150:151]
	s_addc_u32 s13, s77, 0
	s_add_i32 s75, s78, s57
	global_load_lds_dwordx4 v[204:205], off
	v_lshl_add_u64 v[210:211], s[12:13], 0, v[148:149]
	s_mov_b32 m0, s75
	v_lshl_add_u64 v[212:213], s[12:13], 0, v[150:151]
	global_load_lds_dwordx4 v[210:211], off
	s_add_i32 m0, s75, 0x2000
	v_lshl_add_u64 v[244:245], s[28:29], 0, v[136:137]
	global_load_lds_dwordx4 v[212:213], off
	s_mov_b32 m0, s58
	v_lshl_add_u64 v[246:247], s[28:29], 0, v[138:139]
	global_load_lds_dwordx4 v[244:245], off
	s_mov_b32 m0, s59
	s_nop 0
	global_load_lds_dwordx4 v[246:247], off
	s_waitcnt vmcnt(8)
	s_waitcnt lgkmcnt(0)
	s_barrier
; #define PG8_STAGE(bufoff, gbase, voff) do { _Pragma("unroll") for (int _i = 0; _i < 2; ++_i) \
;         __builtin_amdgcn_global_load_lds((const unsigned*)((const char*)(gbase) + (voff)[_i]), (LAS unsigned*)(lds + (bufoff) + ldsw + _i * 8192), 16, 0, 0); } while (0)
; #define PG8_LDA(dst, b, h) do { _Pragma("unroll") for (int m = 0; m < 4; ++m) _Pragma("unroll") for (int k = 0; k < 2; ++k) dst[m][k] = *(const LAS bf16x8*)(lds + PG8_SA(b, h) + aoff + m * 2048 + k * 1024); } while (0)
; #define PG8_LDB(dst, b, h) do { _Pragma("unroll") for (int n = 0; n < 2; ++n) _Pragma("unroll") for (int k = 0; k < 2; ++k) dst[n][k] = *(const LAS bf16x8*)(lds + PG8_SB(b, h) + boff + n * 2048 + k * 1024); } while (0)
; #define PG8_MMA(ai, bj, At, Bt) do { __builtin_amdgcn_s_setprio(1); _Pragma("unroll") for (int m = 0; m < 4; ++m) _Pragma("unroll") for (int n = 0; n < 2; ++n) _Pragma("unroll") for (int k = 0; k < 2; ++k) \
;         acc[ai][bj][m][n] = __builtin_amdgcn_mfma_f32_16x16x32_bf16(Bt[n][k], At[m][k], acc[ai][bj][m][n], 0, 0, 0); __builtin_amdgcn_s_setprio(0); } while (0)
; #define PG8_WAIT_V(n) asm volatile("s_waitcnt vmcnt(" #n ")" ::: "memory")
; #define PG8_WAIT_L(n) asm volatile("s_waitcnt lgkmcnt(" #n ")" ::: "memory")
; #define PG8_BAR __builtin_amdgcn_s_barrier()
; #define PG8_SCHED __builtin_amdgcn_sched_barrier(0)
; template <class Epi, class Sched, bool ALIGN_EPI>
; __device__ __forceinline__ void gemm_phase(LAS unsigned char* lds, const Gemm g, const Sched& S, const Epi& E, const int tid) {
;     ...
;             PG8_WAIT_V(8); PG8_WAIT_L(0); PG8_BAR; PG8_MMA(1, 0, At, B0); PG8_MMA(1, 1, At, B1); PG8_BAR; PG8_SCHED;
;             PG8_LDB(B0, 1, 0); PG8_LDB(B1, 1, 1); PG8_SCHED; PG8_LDA(At, 1, 0); PG8_STAGE(PG8_SA(0, 1), a2 + hstepA, voffA);
;             PG8_WAIT_V(8); PG8_WAIT_L(0); PG8_BAR; PG8_MMA(0, 0, At, B0); PG8_MMA(0, 1, At, B1); PG8_BAR; PG8_SCHED;
	s_setprio 1
	s_waitcnt lgkmcnt(0)
	v_mfma_f32_16x16x32_bf16 v[92:95], v[128:131], v[198:201], v[92:95]
	v_mfma_f32_16x16x32_bf16 v[88:91], v[156:159], v[198:201], v[88:91]
	v_mfma_f32_16x16x32_bf16 v[84:87], v[128:131], v[220:223], v[84:87]
	v_mfma_f32_16x16x32_bf16 v[80:83], v[156:159], v[220:223], v[80:83]
	v_mfma_f32_16x16x32_bf16 v[76:79], v[128:131], v[228:231], v[76:79]
	v_mfma_f32_16x16x32_bf16 v[72:75], v[156:159], v[228:231], v[72:75]
	v_mfma_f32_16x16x32_bf16 v[68:71], v[128:131], v[236:239], v[68:71]
	v_mfma_f32_16x16x32_bf16 v[64:67], v[156:159], v[236:239], v[64:67]
	v_mfma_f32_16x16x32_bf16 v[92:95], v[132:135], v[216:219], v[92:95]
	v_mfma_f32_16x16x32_bf16 v[88:91], v[160:163], v[216:219], v[88:91]
	v_mfma_f32_16x16x32_bf16 v[84:87], v[132:135], v[224:227], v[84:87]
	v_mfma_f32_16x16x32_bf16 v[80:83], v[160:163], v[224:227], v[80:83]
	v_mfma_f32_16x16x32_bf16 v[76:79], v[132:135], v[232:235], v[76:79]
	v_mfma_f32_16x16x32_bf16 v[72:75], v[160:163], v[232:235], v[72:75]
	v_mfma_f32_16x16x32_bf16 v[68:71], v[132:135], v[240:243], v[68:71]
	v_mfma_f32_16x16x32_bf16 v[64:67], v[160:163], v[240:243], v[64:67]
	v_mfma_f32_16x16x32_bf16 v[28:31], v[172:175], v[198:201], v[28:31]
	v_mfma_f32_16x16x32_bf16 v[24:27], v[190:193], v[198:201], v[24:27]
	v_mfma_f32_16x16x32_bf16 v[20:23], v[172:175], v[220:223], v[20:23]
	v_mfma_f32_16x16x32_bf16 v[16:19], v[190:193], v[220:223], v[16:19]
	v_mfma_f32_16x16x32_bf16 v[12:15], v[172:175], v[228:231], v[12:15]
	v_mfma_f32_16x16x32_bf16 v[8:11], v[190:193], v[228:231], v[8:11]
	v_mfma_f32_16x16x32_bf16 v[4:7], v[172:175], v[236:239], v[4:7]
	v_mfma_f32_16x16x32_bf16 v[0:3], v[190:193], v[236:239], v[0:3]
	v_mfma_f32_16x16x32_bf16 v[28:31], v[176:179], v[216:219], v[28:31]
	v_mfma_f32_16x16x32_bf16 v[24:27], v[194:197], v[216:219], v[24:27]
	v_mfma_f32_16x16x32_bf16 v[20:23], v[176:179], v[224:227], v[20:23]
	v_mfma_f32_16x16x32_bf16 v[16:19], v[194:197], v[224:227], v[16:19]
	v_mfma_f32_16x16x32_bf16 v[12:15], v[176:179], v[232:235], v[12:15]
	v_mfma_f32_16x16x32_bf16 v[8:11], v[194:197], v[232:235], v[8:11]
	v_mfma_f32_16x16x32_bf16 v[4:7], v[176:179], v[240:243], v[4:7]
	v_mfma_f32_16x16x32_bf16 v[0:3], v[194:197], v[240:243], v[0:3]
	s_setprio 0
	s_barrier
	s_add_i32 s75, 0, 0x18000
	s_add_i32 s76, 0, 0x1c000
	v_add_u32_e32 v160, s75, v189
	v_add_u32_e32 v164, s76, v189
	ds_read_b128 v[128:131], v160
	ds_read_b128 v[132:135], v160 offset:1024
	ds_read_b128 v[156:159], v160 offset:2048
	ds_read_b128 v[160:163], v160 offset:3072
	ds_read_b128 v[172:175], v164
	ds_read_b128 v[176:179], v164 offset:1024
	ds_read_b128 v[190:193], v164 offset:2048
	ds_read_b128 v[194:197], v164 offset:3072
	s_add_u32 s12, s28, 0x90000
	s_addc_u32 s13, s29, 0
	s_mov_b32 m0, s60
	v_lshl_add_u64 v[248:249], s[12:13], 0, v[136:137]
	ds_read_b128 v[198:201], v147 offset:32768
	ds_read_b128 v[216:219], v147 offset:33792
	ds_read_b128 v[220:223], v147 offset:34816
	ds_read_b128 v[224:227], v147 offset:35840
	ds_read_b128 v[228:231], v147 offset:36864
	ds_read_b128 v[232:235], v147 offset:37888
	ds_read_b128 v[236:239], v147 offset:38912
	ds_read_b128 v[240:243], v147 offset:39936
	global_load_lds_dwordx4 v[248:249], off
	v_lshl_add_u64 v[248:249], s[12:13], 0, v[138:139]
	s_mov_b32 m0, s61
	s_nop 0
	global_load_lds_dwordx4 v[248:249], off
	s_waitcnt vmcnt(8)
	s_waitcnt lgkmcnt(0)
	s_barrier
	s_setprio 1
	s_waitcnt lgkmcnt(0)
	v_mfma_f32_16x16x32_bf16 v[124:127], v[128:131], v[198:201], v[124:127]
	v_mfma_f32_16x16x32_bf16 v[120:123], v[156:159], v[198:201], v[120:123]
	v_mfma_f32_16x16x32_bf16 v[116:119], v[128:131], v[220:223], v[116:119]
	v_mfma_f32_16x16x32_bf16 v[112:115], v[156:159], v[220:223], v[112:115]
	v_mfma_f32_16x16x32_bf16 v[108:111], v[128:131], v[228:231], v[108:111]
	v_mfma_f32_16x16x32_bf16 v[104:107], v[156:159], v[228:231], v[104:107]
	v_mfma_f32_16x16x32_bf16 v[100:103], v[128:131], v[236:239], v[100:103]
	v_mfma_f32_16x16x32_bf16 v[96:99], v[156:159], v[236:239], v[96:99]
	v_mfma_f32_16x16x32_bf16 v[124:127], v[132:135], v[216:219], v[124:127]
	v_mfma_f32_16x16x32_bf16 v[120:123], v[160:163], v[216:219], v[120:123]
	v_mfma_f32_16x16x32_bf16 v[116:119], v[132:135], v[224:227], v[116:119]
	v_mfma_f32_16x16x32_bf16 v[112:115], v[160:163], v[224:227], v[112:115]
	v_mfma_f32_16x16x32_bf16 v[108:111], v[132:135], v[232:235], v[108:111]
	v_mfma_f32_16x16x32_bf16 v[104:107], v[160:163], v[232:235], v[104:107]
	v_mfma_f32_16x16x32_bf16 v[100:103], v[132:135], v[240:243], v[100:103]
	v_mfma_f32_16x16x32_bf16 v[96:99], v[160:163], v[240:243], v[96:99]
	v_mfma_f32_16x16x32_bf16 v[60:63], v[172:175], v[198:201], v[60:63]
	v_mfma_f32_16x16x32_bf16 v[56:59], v[190:193], v[198:201], v[56:59]
	v_mfma_f32_16x16x32_bf16 v[52:55], v[172:175], v[220:223], v[52:55]
	v_mfma_f32_16x16x32_bf16 v[48:51], v[190:193], v[220:223], v[48:51]
	v_mfma_f32_16x16x32_bf16 v[44:47], v[172:175], v[228:231], v[44:47]
	v_mfma_f32_16x16x32_bf16 v[40:43], v[190:193], v[228:231], v[40:43]
	v_mfma_f32_16x16x32_bf16 v[36:39], v[172:175], v[236:239], v[36:39]
	v_mfma_f32_16x16x32_bf16 v[32:35], v[190:193], v[236:239], v[32:35]
	v_mfma_f32_16x16x32_bf16 v[60:63], v[176:179], v[216:219], v[60:63]
	v_mfma_f32_16x16x32_bf16 v[56:59], v[194:197], v[216:219], v[56:59]
	v_mfma_f32_16x16x32_bf16 v[52:55], v[176:179], v[224:227], v[52:55]
	v_mfma_f32_16x16x32_bf16 v[48:51], v[194:197], v[224:227], v[48:51]
	v_mfma_f32_16x16x32_bf16 v[44:47], v[176:179], v[232:235], v[44:47]
	v_mfma_f32_16x16x32_bf16 v[40:43], v[194:197], v[232:235], v[40:43]
	v_mfma_f32_16x16x32_bf16 v[36:39], v[176:179], v[240:243], v[36:39]
	v_mfma_f32_16x16x32_bf16 v[32:35], v[194:197], v[240:243], v[32:35]
	s_setprio 0
	s_barrier
; #define PG8_STAGE(bufoff, gbase, voff) do { _Pragma("unroll") for (int _i = 0; _i < 2; ++_i) \
;         __builtin_amdgcn_global_load_lds((const unsigned*)((const char*)(gbase) + (voff)[_i]), (LAS unsigned*)(lds + (bufoff) + ldsw + _i * 8192), 16, 0, 0); } while (0)
; #define PG8_LDA(dst, b, h) do { _Pragma("unroll") for (int m = 0; m < 4; ++m) _Pragma("unroll") for (int k = 0; k < 2; ++k) dst[m][k] = *(const LAS bf16x8*)(lds + PG8_SA(b, h) + aoff + m * 2048 + k * 1024); } while (0)
; #define PG8_MMA(ai, bj, At, Bt) do { __builtin_amdgcn_s_setprio(1); _Pragma("unroll") for (int m = 0; m < 4; ++m) _Pragma("unroll") for (int n = 0; n < 2; ++n) _Pragma("unroll") for (int k = 0; k < 2; ++k) \
;         acc[ai][bj][m][n] = __builtin_amdgcn_mfma_f32_16x16x32_bf16(Bt[n][k], At[m][k], acc[ai][bj][m][n], 0, 0, 0); __builtin_amdgcn_s_setprio(0); } while (0)
; #define PG8_WAIT_V(n) asm volatile("s_waitcnt vmcnt(" #n ")" ::: "memory")
; #define PG8_WAIT_L(n) asm volatile("s_waitcnt lgkmcnt(" #n ")" ::: "memory")
; #define PG8_BAR __builtin_amdgcn_s_barrier()
; #define PG8_SCHED __builtin_amdgcn_sched_barrier(0)
; template <class Epi, class Sched, bool ALIGN_EPI>
; __device__ __forceinline__ void gemm_phase(LAS unsigned char* lds, const Gemm g, const Sched& S, const Epi& E, const int tid) {
;     ...
;             PG8_LDA(At, 1, 1); PG8_STAGE(PG8_SB(1, 0), b3, voffB); PG8_STAGE(PG8_SB(1, 1), b3 + hstepB, voffB); PG8_STAGE(PG8_SA(1, 0), a3, voffA);
;             PG8_WAIT_V(8); PG8_WAIT_L(0); PG8_BAR; PG8_MMA(1, 0, At, B0); PG8_MMA(1, 1, At, B1); PG8_BAR; PG8_SCHED;
;         }
;         if constexpr (ALIGN_EPI) { if (wr == 0) PG8_BAR; }
	s_add_i32 s12, s75, s57
	v_lshl_add_u64 v[202:203], v[202:203], 0, s[2:3]
	s_mov_b32 m0, s12
	ds_read_b128 v[198:201], v147 offset:49152
	ds_read_b128 v[216:219], v147 offset:50176
	ds_read_b128 v[220:223], v147 offset:51200
	ds_read_b128 v[224:227], v147 offset:52224
	ds_read_b128 v[228:231], v147 offset:53248
	ds_read_b128 v[232:235], v147 offset:54272
	ds_read_b128 v[236:239], v147 offset:55296
	ds_read_b128 v[240:243], v147 offset:56320
	global_load_lds_dwordx4 v[202:203], off
	v_lshl_add_u64 v[202:203], v[204:205], 0, s[2:3]
	s_add_i32 m0, s12, 0x2000
	s_add_i32 s12, s76, s57
	global_load_lds_dwordx4 v[202:203], off
	v_lshl_add_u64 v[202:203], v[210:211], 0, s[2:3]
	s_mov_b32 m0, s12
	s_nop 0
	global_load_lds_dwordx4 v[202:203], off
	v_lshl_add_u64 v[202:203], v[212:213], 0, s[2:3]
	s_add_i32 m0, s12, 0x2000
	s_nop 0
	global_load_lds_dwordx4 v[202:203], off
	v_lshl_add_u64 v[202:203], v[244:245], 0, s[2:3]
	s_mov_b32 m0, s62
	s_nop 0
	global_load_lds_dwordx4 v[202:203], off
	v_lshl_add_u64 v[202:203], v[246:247], 0, s[2:3]
	s_mov_b32 m0, s63
	s_nop 0
	global_load_lds_dwordx4 v[202:203], off
	s_waitcnt vmcnt(8)
	s_waitcnt lgkmcnt(0)
	s_barrier
	s_setprio 1
	s_waitcnt lgkmcnt(0)
	v_mfma_f32_16x16x32_bf16 v[92:95], v[128:131], v[198:201], v[92:95]
	v_mfma_f32_16x16x32_bf16 v[88:91], v[156:159], v[198:201], v[88:91]
	v_mfma_f32_16x16x32_bf16 v[84:87], v[128:131], v[220:223], v[84:87]
	v_mfma_f32_16x16x32_bf16 v[80:83], v[156:159], v[220:223], v[80:83]
	v_mfma_f32_16x16x32_bf16 v[76:79], v[128:131], v[228:231], v[76:79]
	v_mfma_f32_16x16x32_bf16 v[72:75], v[156:159], v[228:231], v[72:75]
	v_mfma_f32_16x16x32_bf16 v[68:71], v[128:131], v[236:239], v[68:71]
	v_mfma_f32_16x16x32_bf16 v[64:67], v[156:159], v[236:239], v[64:67]
	v_mfma_f32_16x16x32_bf16 v[92:95], v[132:135], v[216:219], v[92:95]
	v_mfma_f32_16x16x32_bf16 v[88:91], v[160:163], v[216:219], v[88:91]
	v_mfma_f32_16x16x32_bf16 v[84:87], v[132:135], v[224:227], v[84:87]
	v_mfma_f32_16x16x32_bf16 v[80:83], v[160:163], v[224:227], v[80:83]
	v_mfma_f32_16x16x32_bf16 v[76:79], v[132:135], v[232:235], v[76:79]
	v_mfma_f32_16x16x32_bf16 v[72:75], v[160:163], v[232:235], v[72:75]
	v_mfma_f32_16x16x32_bf16 v[68:71], v[132:135], v[240:243], v[68:71]
	v_mfma_f32_16x16x32_bf16 v[64:67], v[160:163], v[240:243], v[64:67]
	v_mfma_f32_16x16x32_bf16 v[28:31], v[172:175], v[198:201], v[28:31]
	v_mfma_f32_16x16x32_bf16 v[24:27], v[190:193], v[198:201], v[24:27]
	v_mfma_f32_16x16x32_bf16 v[20:23], v[172:175], v[220:223], v[20:23]
	v_mfma_f32_16x16x32_bf16 v[16:19], v[190:193], v[220:223], v[16:19]
	v_mfma_f32_16x16x32_bf16 v[12:15], v[172:175], v[228:231], v[12:15]
	v_mfma_f32_16x16x32_bf16 v[8:11], v[190:193], v[228:231], v[8:11]
	v_mfma_f32_16x16x32_bf16 v[4:7], v[172:175], v[236:239], v[4:7]
	v_mfma_f32_16x16x32_bf16 v[0:3], v[190:193], v[236:239], v[0:3]
	v_mfma_f32_16x16x32_bf16 v[28:31], v[176:179], v[216:219], v[28:31]
	v_mfma_f32_16x16x32_bf16 v[24:27], v[194:197], v[216:219], v[24:27]
	v_mfma_f32_16x16x32_bf16 v[20:23], v[176:179], v[224:227], v[20:23]
	v_mfma_f32_16x16x32_bf16 v[16:19], v[194:197], v[224:227], v[16:19]
	v_mfma_f32_16x16x32_bf16 v[12:15], v[176:179], v[232:235], v[12:15]
	v_mfma_f32_16x16x32_bf16 v[8:11], v[194:197], v[232:235], v[8:11]
	v_mfma_f32_16x16x32_bf16 v[4:7], v[176:179], v[240:243], v[4:7]
	v_mfma_f32_16x16x32_bf16 v[0:3], v[194:197], v[240:243], v[0:3]
	s_setprio 0
	s_barrier
	s_add_u32 s31, s31, 0x100
	s_addc_u32 s73, s73, 0
	s_cmp_ge_u32 s74, s65
	s_mov_b64 s[12:13], s[10:11]
	s_mov_b32 s28, s74
	s_cbranch_scc0 .LBB0_356
	s_and_b64 vcc, exec, s[22:23]
	s_cbranch_vccz .LBB0_359
	s_barrier

; #define PG8_STAGE(bufoff, gbase, voff) do { _Pragma("unroll") for (int _i = 0; _i < 2; ++_i) \
;         __builtin_amdgcn_global_load_lds((const unsigned*)((const char*)(gbase) + (voff)[_i]), (LAS unsigned*)(lds + (bufoff) + ldsw + _i * 8192), 16, 0, 0); } while (0)
; #define PG8_LDA(dst, b, h) do { _Pragma("unroll") for (int m = 0; m < 4; ++m) _Pragma("unroll") for (int k = 0; k < 2; ++k) dst[m][k] = *(const LAS bf16x8*)(lds + PG8_SA(b, h) + aoff + m * 2048 + k * 1024); } while (0)
; #define PG8_LDB(dst, b, h) do { _Pragma("unroll") for (int n = 0; n < 2; ++n) _Pragma("unroll") for (int k = 0; k < 2; ++k) dst[n][k] = *(const LAS bf16x8*)(lds + PG8_SB(b, h) + boff + n * 2048 + k * 1024); } while (0)
; #define PG8_MMA(ai, bj, At, Bt) do { __builtin_amdgcn_s_setprio(1); _Pragma("unroll") for (int m = 0; m < 4; ++m) _Pragma("unroll") for (int n = 0; n < 2; ++n) _Pragma("unroll") for (int k = 0; k < 2; ++k) \
;         acc[ai][bj][m][n] = __builtin_amdgcn_mfma_f32_16x16x32_bf16(Bt[n][k], At[m][k], acc[ai][bj][m][n], 0, 0, 0); __builtin_amdgcn_s_setprio(0); } while (0)
; #define PG8_WAIT_V(n) asm volatile("s_waitcnt vmcnt(" #n ")" ::: "memory")
; #define PG8_WAIT_L(n) asm volatile("s_waitcnt lgkmcnt(" #n ")" ::: "memory")
; template <class Epi, class Sched, bool ALIGN_EPI>
; __device__ __forceinline__ void gemm_phase(LAS unsigned char* lds, const Gemm g, const Sched& S, const Epi& E, const int tid) {
;     ...
;         const bool has_next = S.next(ui + 1, nxt);
;         const char* nA = has_next ? (const char*)g.A + (size_t)nxt.pm * tstepA : cA; const char* nB = has_next ? (const char*)g.Bt + (size_t)nxt.pn * tstepB : cB;
;         for (int t = 0; t < nt; t += 2) {
;             const bool last = (t == nt - 2);
;             const char* a1 = cA + (size_t)(t + 1) * kstep;
;             const char* a2 = last ? nA : cA + (size_t)(t + 2) * kstep; const char* b2 = last ? nB : cB + (size_t)(t + 2) * kstep;
;             const char* a3 = a2 + kstep; const char* b3 = b2 + kstep;
;             PG8_LDB(B0, 0, 0); PG8_LDB(B1, 0, 1); PG8_SCHED; PG8_LDA(At, 0, 0); PG8_STAGE(PG8_SA(1, 1), a1 + hstepA, voffA);
;             PG8_WAIT_V(8); PG8_WAIT_L(0); PG8_BAR; PG8_MMA(0, 0, At, B0); PG8_MMA(0, 1, At, B1); PG8_BAR; PG8_SCHED;
;             PG8_LDA(At, 0, 1); PG8_STAGE(PG8_SB(0, 0), b2, voffB); PG8_STAGE(PG8_SB(0, 1), b2 + hstepB, voffB); PG8_STAGE(PG8_SA(0, 0), a2, voffA);
.LBB0_615:
	s_add_i32 s52, s24, 2
	s_add_u32 s53, s22, 0x80
	s_addc_u32 s25, s23, 0
	s_add_i32 s56, 0, 0x10000
	s_cmp_eq_u32 s43, s24
	s_cselect_b32 s25, s9, s25
	s_cselect_b32 s24, s8, s53
	v_add_u32_e32 v143, s56, v141
	s_cselect_b32 s55, s21, s51
	s_cselect_b32 s54, s20, s50
	s_add_i32 s53, 0, 0x14000
	ds_read_b128 v[144:147], v143
	ds_read_b128 v[148:151], v143 offset:1024
	ds_read_b128 v[152:155], v143 offset:2048
	ds_read_b128 v[156:159], v143 offset:3072
	v_add_u32_e32 v143, s53, v141
	ds_read_b128 v[160:163], v143
	ds_read_b128 v[170:173], v143 offset:1024
	ds_read_b128 v[174:177], v143 offset:2048
	ds_read_b128 v[178:181], v143 offset:3072
	v_lshl_add_u64 v[202:203], s[22:23], 0, v[136:137]
	s_add_i32 m0, s35, 0xc000
	ds_read_b128 v[182:185], v142
	ds_read_b128 v[186:189], v142 offset:1024
	ds_read_b128 v[190:193], v142 offset:2048
	ds_read_b128 v[194:197], v142 offset:3072
	ds_read_b128 v[198:201], v142 offset:4096
	ds_read_b128 v[216:219], v142 offset:5120
	ds_read_b128 v[220:223], v142 offset:6144
	ds_read_b128 v[224:227], v142 offset:7168
	global_load_lds_dwordx4 v[202:203], off
	v_lshl_add_u64 v[202:203], s[22:23], 0, v[138:139]
	s_add_i32 m0, s35, 0xe000
	s_nop 0
	global_load_lds_dwordx4 v[202:203], off
	s_waitcnt vmcnt(8)
	s_waitcnt lgkmcnt(0)
	s_barrier
	s_setprio 1
	s_waitcnt lgkmcnt(0)
	v_mfma_f32_16x16x32_bf16 v[124:127], v[144:147], v[182:185], v[124:127]
	v_mfma_f32_16x16x32_bf16 v[120:123], v[152:155], v[182:185], v[120:123]
	v_mfma_f32_16x16x32_bf16 v[116:119], v[144:147], v[190:193], v[116:119]
	v_mfma_f32_16x16x32_bf16 v[112:115], v[152:155], v[190:193], v[112:115]
	v_mfma_f32_16x16x32_bf16 v[108:111], v[144:147], v[198:201], v[108:111]
	v_mfma_f32_16x16x32_bf16 v[104:107], v[152:155], v[198:201], v[104:107]
	v_mfma_f32_16x16x32_bf16 v[100:103], v[144:147], v[220:223], v[100:103]
	v_mfma_f32_16x16x32_bf16 v[96:99], v[152:155], v[220:223], v[96:99]
	v_mfma_f32_16x16x32_bf16 v[124:127], v[148:151], v[186:189], v[124:127]
	v_mfma_f32_16x16x32_bf16 v[120:123], v[156:159], v[186:189], v[120:123]
	v_mfma_f32_16x16x32_bf16 v[116:119], v[148:151], v[194:197], v[116:119]
	v_mfma_f32_16x16x32_bf16 v[112:115], v[156:159], v[194:197], v[112:115]
	v_mfma_f32_16x16x32_bf16 v[108:111], v[148:151], v[216:219], v[108:111]
	v_mfma_f32_16x16x32_bf16 v[104:107], v[156:159], v[216:219], v[104:107]
	v_mfma_f32_16x16x32_bf16 v[100:103], v[148:151], v[224:227], v[100:103]
	v_mfma_f32_16x16x32_bf16 v[96:99], v[156:159], v[224:227], v[96:99]
	v_mfma_f32_16x16x32_bf16 v[68:71], v[160:163], v[182:185], v[68:71]
	v_mfma_f32_16x16x32_bf16 v[64:67], v[174:177], v[182:185], v[64:67]
	v_mfma_f32_16x16x32_bf16 v[52:55], v[160:163], v[190:193], v[52:55]
	v_mfma_f32_16x16x32_bf16 v[48:51], v[174:177], v[190:193], v[48:51]
	v_mfma_f32_16x16x32_bf16 v[44:47], v[160:163], v[198:201], v[44:47]
	v_mfma_f32_16x16x32_bf16 v[40:43], v[174:177], v[198:201], v[40:43]
	v_mfma_f32_16x16x32_bf16 v[36:39], v[160:163], v[220:223], v[36:39]
	v_mfma_f32_16x16x32_bf16 v[32:35], v[174:177], v[220:223], v[32:35]
	v_mfma_f32_16x16x32_bf16 v[68:71], v[170:173], v[186:189], v[68:71]
	v_mfma_f32_16x16x32_bf16 v[64:67], v[178:181], v[186:189], v[64:67]
	v_mfma_f32_16x16x32_bf16 v[52:55], v[170:173], v[194:197], v[52:55]
	v_mfma_f32_16x16x32_bf16 v[48:51], v[178:181], v[194:197], v[48:51]
	v_mfma_f32_16x16x32_bf16 v[44:47], v[170:173], v[216:219], v[44:47]
	v_mfma_f32_16x16x32_bf16 v[40:43], v[178:181], v[216:219], v[40:43]
	v_mfma_f32_16x16x32_bf16 v[36:39], v[170:173], v[224:227], v[36:39]
	v_mfma_f32_16x16x32_bf16 v[32:35], v[178:181], v[224:227], v[32:35]
	s_setprio 0
	s_barrier
	s_add_i32 s56, s56, s29
	v_lshl_add_u64 v[202:203], s[54:55], 0, v[164:165]
	s_mov_b32 m0, s56
	ds_read_b128 v[182:185], v142 offset:16384
	ds_read_b128 v[186:189], v142 offset:17408
	ds_read_b128 v[190:193], v142 offset:18432
	ds_read_b128 v[194:197], v142 offset:19456
	ds_read_b128 v[198:201], v142 offset:20480
	ds_read_b128 v[216:219], v142 offset:21504
	ds_read_b128 v[220:223], v142 offset:22528
	ds_read_b128 v[224:227], v142 offset:23552
	global_load_lds_dwordx4 v[202:203], off
	s_add_i32 m0, s56, 0x2000
	v_lshl_add_u64 v[204:205], s[54:55], 0, v[128:129]
	s_add_u32 s54, s54, s94
	s_addc_u32 s55, s55, 0
	s_add_i32 s53, s53, s29
	global_load_lds_dwordx4 v[204:205], off
	v_lshl_add_u64 v[210:211], s[54:55], 0, v[164:165]
	s_mov_b32 m0, s53
	v_lshl_add_u64 v[212:213], s[54:55], 0, v[128:129]
	global_load_lds_dwordx4 v[210:211], off
	s_add_i32 m0, s53, 0x2000
	v_lshl_add_u64 v[228:229], s[24:25], 0, v[132:133]
	global_load_lds_dwordx4 v[212:213], off
	s_mov_b32 m0, s35
	v_lshl_add_u64 v[230:231], s[24:25], 0, v[130:131]
	global_load_lds_dwordx4 v[228:229], off
	s_mov_b32 m0, s36
	s_nop 0
	global_load_lds_dwordx4 v[230:231], off
	s_waitcnt vmcnt(8)
	s_waitcnt lgkmcnt(0)
	s_barrier
; #define PG8_STAGE(bufoff, gbase, voff) do { _Pragma("unroll") for (int _i = 0; _i < 2; ++_i) \
;         __builtin_amdgcn_global_load_lds((const unsigned*)((const char*)(gbase) + (voff)[_i]), (LAS unsigned*)(lds + (bufoff) + ldsw + _i * 8192), 16, 0, 0); } while (0)
; #define PG8_LDA(dst, b, h) do { _Pragma("unroll") for (int m = 0; m < 4; ++m) _Pragma("unroll") for (int k = 0; k < 2; ++k) dst[m][k] = *(const LAS bf16x8*)(lds + PG8_SA(b, h) + aoff + m * 2048 + k * 1024); } while (0)
; #define PG8_LDB(dst, b, h) do { _Pragma("unroll") for (int n = 0; n < 2; ++n) _Pragma("unroll") for (int k = 0; k < 2; ++k) dst[n][k] = *(const LAS bf16x8*)(lds + PG8_SB(b, h) + boff + n * 2048 + k * 1024); } while (0)
; #define PG8_MMA(ai, bj, At, Bt) do { __builtin_amdgcn_s_setprio(1); _Pragma("unroll") for (int m = 0; m < 4; ++m) _Pragma("unroll") for (int n = 0; n < 2; ++n) _Pragma("unroll") for (int k = 0; k < 2; ++k) \
;         acc[ai][bj][m][n] = __builtin_amdgcn_mfma_f32_16x16x32_bf16(Bt[n][k], At[m][k], acc[ai][bj][m][n], 0, 0, 0); __builtin_amdgcn_s_setprio(0); } while (0)
; #define PG8_WAIT_V(n) asm volatile("s_waitcnt vmcnt(" #n ")" ::: "memory")
; #define PG8_WAIT_L(n) asm volatile("s_waitcnt lgkmcnt(" #n ")" ::: "memory")
; #define PG8_BAR __builtin_amdgcn_s_barrier()
; #define PG8_SCHED __builtin_amdgcn_sched_barrier(0)
; template <class Epi, class Sched, bool ALIGN_EPI>
; __device__ __forceinline__ void gemm_phase(LAS unsigned char* lds, const Gemm g, const Sched& S, const Epi& E, const int tid) {
;     ...
;             PG8_WAIT_V(8); PG8_WAIT_L(0); PG8_BAR; PG8_MMA(1, 0, At, B0); PG8_MMA(1, 1, At, B1); PG8_BAR; PG8_SCHED;
;             PG8_LDB(B0, 1, 0); PG8_LDB(B1, 1, 1); PG8_SCHED; PG8_LDA(At, 1, 0); PG8_STAGE(PG8_SA(0, 1), a2 + hstepA, voffA);
;             PG8_WAIT_V(8); PG8_WAIT_L(0); PG8_BAR; PG8_MMA(0, 0, At, B0); PG8_MMA(0, 1, At, B1); PG8_BAR; PG8_SCHED;
	s_setprio 1
	s_waitcnt lgkmcnt(0)
	v_mfma_f32_16x16x32_bf16 v[92:95], v[144:147], v[182:185], v[92:95]
	v_mfma_f32_16x16x32_bf16 v[88:91], v[152:155], v[182:185], v[88:91]
	v_mfma_f32_16x16x32_bf16 v[84:87], v[144:147], v[190:193], v[84:87]
	v_mfma_f32_16x16x32_bf16 v[80:83], v[152:155], v[190:193], v[80:83]
	v_mfma_f32_16x16x32_bf16 v[76:79], v[144:147], v[198:201], v[76:79]
	v_mfma_f32_16x16x32_bf16 v[72:75], v[152:155], v[198:201], v[72:75]
	v_mfma_f32_16x16x32_bf16 v[60:63], v[144:147], v[220:223], v[60:63]
	v_mfma_f32_16x16x32_bf16 v[56:59], v[152:155], v[220:223], v[56:59]
	v_mfma_f32_16x16x32_bf16 v[92:95], v[148:151], v[186:189], v[92:95]
	v_mfma_f32_16x16x32_bf16 v[88:91], v[156:159], v[186:189], v[88:91]
	v_mfma_f32_16x16x32_bf16 v[84:87], v[148:151], v[194:197], v[84:87]
	v_mfma_f32_16x16x32_bf16 v[80:83], v[156:159], v[194:197], v[80:83]
	v_mfma_f32_16x16x32_bf16 v[76:79], v[148:151], v[216:219], v[76:79]
	v_mfma_f32_16x16x32_bf16 v[72:75], v[156:159], v[216:219], v[72:75]
	v_mfma_f32_16x16x32_bf16 v[60:63], v[148:151], v[224:227], v[60:63]
	v_mfma_f32_16x16x32_bf16 v[56:59], v[156:159], v[224:227], v[56:59]
	v_mfma_f32_16x16x32_bf16 v[28:31], v[160:163], v[182:185], v[28:31]
	v_mfma_f32_16x16x32_bf16 v[24:27], v[174:177], v[182:185], v[24:27]
	v_mfma_f32_16x16x32_bf16 v[20:23], v[160:163], v[190:193], v[20:23]
	v_mfma_f32_16x16x32_bf16 v[16:19], v[174:177], v[190:193], v[16:19]
	v_mfma_f32_16x16x32_bf16 v[12:15], v[160:163], v[198:201], v[12:15]
	v_mfma_f32_16x16x32_bf16 v[8:11], v[174:177], v[198:201], v[8:11]
	v_mfma_f32_16x16x32_bf16 v[4:7], v[160:163], v[220:223], v[4:7]
	v_mfma_f32_16x16x32_bf16 v[0:3], v[174:177], v[220:223], v[0:3]
	v_mfma_f32_16x16x32_bf16 v[28:31], v[170:173], v[186:189], v[28:31]
	v_mfma_f32_16x16x32_bf16 v[24:27], v[178:181], v[186:189], v[24:27]
	v_mfma_f32_16x16x32_bf16 v[20:23], v[170:173], v[194:197], v[20:23]
	v_mfma_f32_16x16x32_bf16 v[16:19], v[178:181], v[194:197], v[16:19]
	v_mfma_f32_16x16x32_bf16 v[12:15], v[170:173], v[216:219], v[12:15]
	v_mfma_f32_16x16x32_bf16 v[8:11], v[178:181], v[216:219], v[8:11]
	v_mfma_f32_16x16x32_bf16 v[4:7], v[170:173], v[224:227], v[4:7]
	v_mfma_f32_16x16x32_bf16 v[0:3], v[178:181], v[224:227], v[0:3]
	s_setprio 0
	s_barrier
	s_add_i32 s53, 0, 0x18000
	v_add_u32_e32 v143, s53, v141
	s_add_i32 s54, 0, 0x1c000
	ds_read_b128 v[144:147], v143
	ds_read_b128 v[148:151], v143 offset:1024
	ds_read_b128 v[152:155], v143 offset:2048
	ds_read_b128 v[156:159], v143 offset:3072
	v_add_u32_e32 v143, s54, v141
	ds_read_b128 v[160:163], v143
	ds_read_b128 v[170:173], v143 offset:1024
	ds_read_b128 v[174:177], v143 offset:2048
	ds_read_b128 v[178:181], v143 offset:3072
	s_add_u32 s24, s24, s94
	s_addc_u32 s25, s25, 0
	s_mov_b32 m0, s37
	v_lshl_add_u64 v[232:233], s[24:25], 0, v[132:133]
	ds_read_b128 v[182:185], v142 offset:32768
	ds_read_b128 v[186:189], v142 offset:33792
	ds_read_b128 v[190:193], v142 offset:34816
	ds_read_b128 v[194:197], v142 offset:35840
	ds_read_b128 v[198:201], v142 offset:36864
	ds_read_b128 v[216:219], v142 offset:37888
	ds_read_b128 v[220:223], v142 offset:38912
	ds_read_b128 v[224:227], v142 offset:39936
	global_load_lds_dwordx4 v[232:233], off
	v_lshl_add_u64 v[232:233], s[24:25], 0, v[130:131]
	s_mov_b32 m0, s38
	s_nop 0
	global_load_lds_dwordx4 v[232:233], off
	s_waitcnt vmcnt(8)
	s_waitcnt lgkmcnt(0)
	s_barrier
	s_setprio 1
	s_waitcnt lgkmcnt(0)
	v_mfma_f32_16x16x32_bf16 v[124:127], v[144:147], v[182:185], v[124:127]
	v_mfma_f32_16x16x32_bf16 v[120:123], v[152:155], v[182:185], v[120:123]
	v_mfma_f32_16x16x32_bf16 v[116:119], v[144:147], v[190:193], v[116:119]
	v_mfma_f32_16x16x32_bf16 v[112:115], v[152:155], v[190:193], v[112:115]
	v_mfma_f32_16x16x32_bf16 v[108:111], v[144:147], v[198:201], v[108:111]
	v_mfma_f32_16x16x32_bf16 v[104:107], v[152:155], v[198:201], v[104:107]
	v_mfma_f32_16x16x32_bf16 v[100:103], v[144:147], v[220:223], v[100:103]
	v_mfma_f32_16x16x32_bf16 v[96:99], v[152:155], v[220:223], v[96:99]
	v_mfma_f32_16x16x32_bf16 v[124:127], v[148:151], v[186:189], v[124:127]
	v_mfma_f32_16x16x32_bf16 v[120:123], v[156:159], v[186:189], v[120:123]
	v_mfma_f32_16x16x32_bf16 v[116:119], v[148:151], v[194:197], v[116:119]
	v_mfma_f32_16x16x32_bf16 v[112:115], v[156:159], v[194:197], v[112:115]
	v_mfma_f32_16x16x32_bf16 v[108:111], v[148:151], v[216:219], v[108:111]
	v_mfma_f32_16x16x32_bf16 v[104:107], v[156:159], v[216:219], v[104:107]
	v_mfma_f32_16x16x32_bf16 v[100:103], v[148:151], v[224:227], v[100:103]
	v_mfma_f32_16x16x32_bf16 v[96:99], v[156:159], v[224:227], v[96:99]
	v_mfma_f32_16x16x32_bf16 v[68:71], v[160:163], v[182:185], v[68:71]
	v_mfma_f32_16x16x32_bf16 v[64:67], v[174:177], v[182:185], v[64:67]
	v_mfma_f32_16x16x32_bf16 v[52:55], v[160:163], v[190:193], v[52:55]
	v_mfma_f32_16x16x32_bf16 v[48:51], v[174:177], v[190:193], v[48:51]
	v_mfma_f32_16x16x32_bf16 v[44:47], v[160:163], v[198:201], v[44:47]
	v_mfma_f32_16x16x32_bf16 v[40:43], v[174:177], v[198:201], v[40:43]
	v_mfma_f32_16x16x32_bf16 v[36:39], v[160:163], v[220:223], v[36:39]
	v_mfma_f32_16x16x32_bf16 v[32:35], v[174:177], v[220:223], v[32:35]
	v_mfma_f32_16x16x32_bf16 v[68:71], v[170:173], v[186:189], v[68:71]
	v_mfma_f32_16x16x32_bf16 v[64:67], v[178:181], v[186:189], v[64:67]
	v_mfma_f32_16x16x32_bf16 v[52:55], v[170:173], v[194:197], v[52:55]
	v_mfma_f32_16x16x32_bf16 v[48:51], v[178:181], v[194:197], v[48:51]
	v_mfma_f32_16x16x32_bf16 v[44:47], v[170:173], v[216:219], v[44:47]
	v_mfma_f32_16x16x32_bf16 v[40:43], v[178:181], v[216:219], v[40:43]
	v_mfma_f32_16x16x32_bf16 v[36:39], v[170:173], v[224:227], v[36:39]
	v_mfma_f32_16x16x32_bf16 v[32:35], v[178:181], v[224:227], v[32:35]
	s_setprio 0
	s_barrier
; #define PG8_STAGE(bufoff, gbase, voff) do { _Pragma("unroll") for (int _i = 0; _i < 2; ++_i) \
;         __builtin_amdgcn_global_load_lds((const unsigned*)((const char*)(gbase) + (voff)[_i]), (LAS unsigned*)(lds + (bufoff) + ldsw + _i * 8192), 16, 0, 0); } while (0)
; #define PG8_LDA(dst, b, h) do { _Pragma("unroll") for (int m = 0; m < 4; ++m) _Pragma("unroll") for (int k = 0; k < 2; ++k) dst[m][k] = *(const LAS bf16x8*)(lds + PG8_SA(b, h) + aoff + m * 2048 + k * 1024); } while (0)
; #define PG8_MMA(ai, bj, At, Bt) do { __builtin_amdgcn_s_setprio(1); _Pragma("unroll") for (int m = 0; m < 4; ++m) _Pragma("unroll") for (int n = 0; n < 2; ++n) _Pragma("unroll") for (int k = 0; k < 2; ++k) \
;         acc[ai][bj][m][n] = __builtin_amdgcn_mfma_f32_16x16x32_bf16(Bt[n][k], At[m][k], acc[ai][bj][m][n], 0, 0, 0); __builtin_amdgcn_s_setprio(0); } while (0)
; #define PG8_WAIT_V(n) asm volatile("s_waitcnt vmcnt(" #n ")" ::: "memory")
; #define PG8_WAIT_L(n) asm volatile("s_waitcnt lgkmcnt(" #n ")" ::: "memory")
; #define PG8_BAR __builtin_amdgcn_s_barrier()
; #define PG8_SCHED __builtin_amdgcn_sched_barrier(0)
; template <class Epi, class Sched, bool ALIGN_EPI>
; __device__ __forceinline__ void gemm_phase(LAS unsigned char* lds, const Gemm g, const Sched& S, const Epi& E, const int tid) {
;     ...
;             PG8_LDA(At, 1, 1); PG8_STAGE(PG8_SB(1, 0), b3, voffB); PG8_STAGE(PG8_SB(1, 1), b3 + hstepB, voffB); PG8_STAGE(PG8_SA(1, 0), a3, voffA);
;             PG8_WAIT_V(8); PG8_WAIT_L(0); PG8_BAR; PG8_MMA(1, 0, At, B0); PG8_MMA(1, 1, At, B1); PG8_BAR; PG8_SCHED;
;         }
;         if constexpr (ALIGN_EPI) { if (wr == 0) PG8_BAR; }
	s_add_i32 s24, s53, s29
	v_lshl_add_u64 v[202:203], v[202:203], 0, s[2:3]
	s_mov_b32 m0, s24
	ds_read_b128 v[182:185], v142 offset:49152
	ds_read_b128 v[186:189], v142 offset:50176
	ds_read_b128 v[190:193], v142 offset:51200
	ds_read_b128 v[194:197], v142 offset:52224
	ds_read_b128 v[198:201], v142 offset:53248
	ds_read_b128 v[216:219], v142 offset:54272
	ds_read_b128 v[220:223], v142 offset:55296
	ds_read_b128 v[224:227], v142 offset:56320
	global_load_lds_dwordx4 v[202:203], off
	v_lshl_add_u64 v[202:203], v[204:205], 0, s[2:3]
	s_add_i32 m0, s24, 0x2000
	s_add_i32 s24, s54, s29
	global_load_lds_dwordx4 v[202:203], off
	v_lshl_add_u64 v[202:203], v[210:211], 0, s[2:3]
	s_mov_b32 m0, s24
	s_nop 0
	global_load_lds_dwordx4 v[202:203], off
	v_lshl_add_u64 v[202:203], v[212:213], 0, s[2:3]
	s_add_i32 m0, s24, 0x2000
	s_nop 0
	global_load_lds_dwordx4 v[202:203], off
	v_lshl_add_u64 v[202:203], v[228:229], 0, s[2:3]
	s_mov_b32 m0, s39
	s_nop 0
	global_load_lds_dwordx4 v[202:203], off
	v_lshl_add_u64 v[202:203], v[230:231], 0, s[2:3]
	s_mov_b32 m0, s40
	s_nop 0
	global_load_lds_dwordx4 v[202:203], off
	s_waitcnt vmcnt(8)
	s_waitcnt lgkmcnt(0)
	s_barrier
	s_setprio 1
	s_waitcnt lgkmcnt(0)
	v_mfma_f32_16x16x32_bf16 v[92:95], v[144:147], v[182:185], v[92:95]
	v_mfma_f32_16x16x32_bf16 v[88:91], v[152:155], v[182:185], v[88:91]
	v_mfma_f32_16x16x32_bf16 v[84:87], v[144:147], v[190:193], v[84:87]
	v_mfma_f32_16x16x32_bf16 v[80:83], v[152:155], v[190:193], v[80:83]
	v_mfma_f32_16x16x32_bf16 v[76:79], v[144:147], v[198:201], v[76:79]
	v_mfma_f32_16x16x32_bf16 v[72:75], v[152:155], v[198:201], v[72:75]
	v_mfma_f32_16x16x32_bf16 v[60:63], v[144:147], v[220:223], v[60:63]
	v_mfma_f32_16x16x32_bf16 v[56:59], v[152:155], v[220:223], v[56:59]
	v_mfma_f32_16x16x32_bf16 v[92:95], v[148:151], v[186:189], v[92:95]
	v_mfma_f32_16x16x32_bf16 v[88:91], v[156:159], v[186:189], v[88:91]
	v_mfma_f32_16x16x32_bf16 v[84:87], v[148:151], v[194:197], v[84:87]
	v_mfma_f32_16x16x32_bf16 v[80:83], v[156:159], v[194:197], v[80:83]
	v_mfma_f32_16x16x32_bf16 v[76:79], v[148:151], v[216:219], v[76:79]
	v_mfma_f32_16x16x32_bf16 v[72:75], v[156:159], v[216:219], v[72:75]
	v_mfma_f32_16x16x32_bf16 v[60:63], v[148:151], v[224:227], v[60:63]
	v_mfma_f32_16x16x32_bf16 v[56:59], v[156:159], v[224:227], v[56:59]
	v_mfma_f32_16x16x32_bf16 v[28:31], v[160:163], v[182:185], v[28:31]
	v_mfma_f32_16x16x32_bf16 v[24:27], v[174:177], v[182:185], v[24:27]
	v_mfma_f32_16x16x32_bf16 v[20:23], v[160:163], v[190:193], v[20:23]
	v_mfma_f32_16x16x32_bf16 v[16:19], v[174:177], v[190:193], v[16:19]
	v_mfma_f32_16x16x32_bf16 v[12:15], v[160:163], v[198:201], v[12:15]
	v_mfma_f32_16x16x32_bf16 v[8:11], v[174:177], v[198:201], v[8:11]
	v_mfma_f32_16x16x32_bf16 v[4:7], v[160:163], v[220:223], v[4:7]
	v_mfma_f32_16x16x32_bf16 v[0:3], v[174:177], v[220:223], v[0:3]
	v_mfma_f32_16x16x32_bf16 v[28:31], v[170:173], v[186:189], v[28:31]
	v_mfma_f32_16x16x32_bf16 v[24:27], v[178:181], v[186:189], v[24:27]
	v_mfma_f32_16x16x32_bf16 v[20:23], v[170:173], v[194:197], v[20:23]
	v_mfma_f32_16x16x32_bf16 v[16:19], v[178:181], v[194:197], v[16:19]
	v_mfma_f32_16x16x32_bf16 v[12:15], v[170:173], v[216:219], v[12:15]
	v_mfma_f32_16x16x32_bf16 v[8:11], v[178:181], v[216:219], v[8:11]
	v_mfma_f32_16x16x32_bf16 v[4:7], v[170:173], v[224:227], v[4:7]
	v_mfma_f32_16x16x32_bf16 v[0:3], v[178:181], v[224:227], v[0:3]
	s_setprio 0
	s_barrier
	s_add_u32 s22, s22, 0x100
	s_addc_u32 s23, s23, 0
	s_add_u32 s50, s50, 0x100
	s_addc_u32 s51, s51, 0
	s_cmp_ge_u32 s52, s41
	s_mov_b32 s24, s52
	s_cbranch_scc0 .LBB0_615
	s_and_b64 vcc, exec, s[18:19]
	s_cbranch_vccz .LBB0_618
	s_barrier
